# strategy 2 (de-serialisation): first grid barrier reads its 16 census counters together instead of one load + full wait each
# baseline (speedup 1.0000x reference)
.LBB0_25:
	s_mov_b64 s[22:23], -1
	s_mov_b64 s[26:27], -1
	v_readlane_b32 s8, v253, 25
	v_readlane_b32 s9, v253, 26
	s_nop 4
	global_load_dword v0, v1, s[8:9] sc1
	v_readlane_b32 s8, v253, 27
	v_readlane_b32 s9, v253, 28
	s_nop 4
	global_load_dword v2, v1, s[8:9] sc1
	v_readlane_b32 s8, v253, 29
	v_readlane_b32 s9, v253, 30
	s_nop 4
	global_load_dword v3, v1, s[8:9] sc1
	v_readlane_b32 s8, v253, 31
	v_readlane_b32 s9, v253, 32
	s_nop 4
	global_load_dword v4, v1, s[8:9] sc1
	v_readlane_b32 s8, v253, 33
	v_readlane_b32 s9, v253, 34
	s_nop 4
	global_load_dword v5, v1, s[8:9] sc1
	v_readlane_b32 s8, v253, 35
	v_readlane_b32 s9, v253, 36
	s_nop 4
	global_load_dword v6, v1, s[8:9] sc1
	v_readlane_b32 s8, v253, 37
	v_readlane_b32 s9, v253, 38
	s_nop 4
	global_load_dword v7, v1, s[8:9] sc1
	v_readlane_b32 s8, v253, 39
	v_readlane_b32 s9, v253, 40
	s_nop 4
	global_load_dword v8, v1, s[8:9] sc1
	v_readlane_b32 s8, v253, 41
	v_readlane_b32 s9, v253, 42
	s_nop 4
	global_load_dword v9, v1, s[8:9] sc1
	v_readlane_b32 s8, v253, 43
	v_readlane_b32 s9, v253, 44
	s_nop 4
	global_load_dword v10, v1, s[8:9] sc1
	v_readlane_b32 s8, v253, 45
	v_readlane_b32 s9, v253, 46
	s_nop 4
	global_load_dword v11, v1, s[8:9] sc1
	v_readlane_b32 s8, v253, 47
	v_readlane_b32 s9, v253, 48
	s_nop 4
	global_load_dword v12, v1, s[8:9] sc1
	v_readlane_b32 s8, v253, 49
	v_readlane_b32 s9, v253, 50
	s_nop 4
	global_load_dword v13, v1, s[8:9] sc1
	v_readlane_b32 s8, v253, 51
	v_readlane_b32 s9, v253, 52
	s_nop 4
	global_load_dword v14, v1, s[8:9] sc1
	v_readlane_b32 s8, v253, 53
	v_readlane_b32 s9, v253, 54
	s_nop 4
	global_load_dword v15, v1, s[8:9] sc1
	v_readlane_b32 s8, v253, 55
	v_readlane_b32 s9, v253, 56
	s_nop 4
	global_load_dword v16, v1, s[8:9] sc1
	s_waitcnt vmcnt(0)
	v_add_u32_e32 v17, v2, v0
	v_add_u32_e32 v17, v17, v3
	v_add_u32_e32 v17, v17, v4
	v_add_u32_e32 v17, v17, v5
	v_add_u32_e32 v17, v17, v6
	v_add_u32_e32 v17, v17, v7
	v_add_u32_e32 v17, v17, v8
	v_add_u32_e32 v17, v17, v9
	v_add_u32_e32 v17, v17, v10
	v_add_u32_e32 v17, v17, v11
	v_add_u32_e32 v17, v17, v12
	v_add_u32_e32 v17, v17, v13
	v_add_u32_e32 v17, v17, v14
	v_add_u32_e32 v17, v17, v15
	v_add_u32_e32 v17, v17, v16
	v_cmp_eq_u32_e32 vcc, s5, v17
	s_cbranch_vccnz .LBB0_24
	s_and_b32 s8, s6, 0xff
	s_cmp_eq_u32 s8, 0
	s_mov_b64 s[34:35], -1
	s_sleep 1
	s_cbranch_scc0 .LBB0_29
	v_readlane_b32 s8, v253, 23
	v_readlane_b32 s9, v253, 24
	s_nop 4
	global_load_dword v17, v1, s[8:9] sc1
	s_waitcnt vmcnt(0)
	v_cmp_eq_u32_e32 vcc, 0, v17
	s_cbranch_vccnz .LBB0_31
	s_mov_b64 s[34:35], 0
